# in-proj GEMM epilogue: the 8 serialized load->wait->reduce round trips for the row rstd become one batch of 16 loads, one wait, batched cross-lane exchanges (same f32 add order)
# speedup vs baseline: 1.0089x; 1.0089x over previous
.LBB0_120:
	s_lshl_b32 s8, s8, 8
	v_mov_b32_e32 v172, v157
	v_mov_b32_e32 v130, v1
	s_add_i32 s8, s8, s62
	v_and_b32_e32 v134, 64, v169
	v_add_u32_e32 v154, s8, v130
	v_mov_b32_e32 v131, v172
	v_mov_b32_e32 v130, v154
	v_add_u32_e32 v134, 64, v134
	v_lshlrev_b32_e32 v132, 3, v131
	v_xor_b32_e32 v131, 16, v169
	v_cmp_lt_i32_e32 vcc, v131, v134
	v_ashrrev_i32_e32 v133, 31, v132
	v_lshl_add_u64 v[132:133], v[132:133], 2, s[10:11]
	v_cndmask_b32_e32 v131, v169, v131, vcc
	v_lshlrev_b32_e32 v173, 2, v131
	v_xor_b32_e32 v131, 32, v169
	v_cmp_lt_i32_e32 vcc, v131, v134
	v_cndmask_b32_e32 v131, v169, v131, vcc
	v_lshlrev_b32_e32 v155, 2, v131
	v_ashrrev_i32_e32 v131, 31, v130
	v_lshlrev_b64 v[130:131], 7, v[130:131]
	v_lshl_add_u64 v[130:131], v[132:133], 0, v[130:131]
	s_mov_b64 s[8:9], 0x1000
	v_lshl_add_u64 v[132:133], v[130:131], 0, s[8:9]
	global_load_dwordx4 v[174:177], v[130:131], off
	global_load_dwordx4 v[178:181], v[130:131], off offset:16
	global_load_dwordx4 v[182:185], v[130:131], off offset:2048
	global_load_dwordx4 v[186:189], v[130:131], off offset:2064
	s_mov_b64 s[8:9], 0x4000
	v_lshl_add_u64 v[134:135], v[130:131], 0, s[8:9]
	global_load_dwordx4 v[190:193], v[132:133], off
	global_load_dwordx4 v[194:197], v[132:133], off offset:16
	global_load_dwordx4 v[198:201], v[132:133], off offset:2048
	global_load_dwordx4 v[202:205], v[132:133], off offset:2064
	s_mov_b64 s[8:9], 0x5000
	v_lshl_add_u64 v[136:137], v[130:131], 0, s[8:9]
	global_load_dwordx4 v[206:209], v[134:135], off
	global_load_dwordx4 v[210:213], v[134:135], off offset:16
	global_load_dwordx4 v[214:217], v[134:135], off offset:2048
	global_load_dwordx4 v[218:221], v[134:135], off offset:2064
	global_load_dwordx4 v[222:225], v[136:137], off
	global_load_dwordx4 v[226:229], v[136:137], off offset:16
	global_load_dwordx4 v[230:233], v[136:137], off offset:2048
	global_load_dwordx4 v[234:237], v[136:137], off offset:2064
	v_mov_b32_e32 v166, 0x358637bd
	s_waitcnt vmcnt(0)
	v_add_f32_e32 v174, v174, v175
	v_add_f32_e32 v178, v178, v179
	v_add_f32_e32 v182, v182, v183
	v_add_f32_e32 v186, v186, v187
	v_add_f32_e32 v176, v176, v177
	v_add_f32_e32 v180, v180, v181
	v_add_f32_e32 v184, v184, v185
	v_add_f32_e32 v188, v188, v189
	v_add_f32_e32 v174, v174, v176
	v_add_f32_e32 v178, v178, v180
	v_add_f32_e32 v182, v182, v184
	v_add_f32_e32 v186, v186, v188
	v_add_f32_e32 v175, v174, v178
	v_add_f32_e32 v174, v182, v186
	v_add_f32_e32 v190, v190, v191
	v_add_f32_e32 v194, v194, v195
	v_add_f32_e32 v198, v198, v199
	v_add_f32_e32 v202, v202, v203
	v_add_f32_e32 v192, v192, v193
	v_add_f32_e32 v196, v196, v197
	v_add_f32_e32 v200, v200, v201
	v_add_f32_e32 v204, v204, v205
	v_add_f32_e32 v190, v190, v192
	v_add_f32_e32 v194, v194, v196
	v_add_f32_e32 v198, v198, v200
	v_add_f32_e32 v202, v202, v204
	v_add_f32_e32 v191, v190, v194
	v_add_f32_e32 v190, v198, v202
	v_add_f32_e32 v206, v206, v207
	v_add_f32_e32 v210, v210, v211
	v_add_f32_e32 v214, v214, v215
	v_add_f32_e32 v218, v218, v219
	v_add_f32_e32 v208, v208, v209
	v_add_f32_e32 v212, v212, v213
	v_add_f32_e32 v216, v216, v217
	v_add_f32_e32 v220, v220, v221
	v_add_f32_e32 v206, v206, v208
	v_add_f32_e32 v210, v210, v212
	v_add_f32_e32 v214, v214, v216
	v_add_f32_e32 v218, v218, v220
	v_add_f32_e32 v207, v206, v210
	v_add_f32_e32 v206, v214, v218
	v_add_f32_e32 v222, v222, v223
	v_add_f32_e32 v226, v226, v227
	v_add_f32_e32 v230, v230, v231
	v_add_f32_e32 v234, v234, v235
	v_add_f32_e32 v224, v224, v225
	v_add_f32_e32 v228, v228, v229
	v_add_f32_e32 v232, v232, v233
	v_add_f32_e32 v236, v236, v237
	v_add_f32_e32 v222, v222, v224
	v_add_f32_e32 v226, v226, v228
	v_add_f32_e32 v230, v230, v232
	v_add_f32_e32 v234, v234, v236
	v_add_f32_e32 v223, v222, v226
	v_add_f32_e32 v222, v230, v234
	ds_bpermute_b32 v179, v173, v175
	ds_bpermute_b32 v178, v173, v174
	ds_bpermute_b32 v195, v173, v191
	ds_bpermute_b32 v194, v173, v190
	ds_bpermute_b32 v211, v173, v207
	ds_bpermute_b32 v210, v173, v206
	ds_bpermute_b32 v227, v173, v223
	ds_bpermute_b32 v226, v173, v222
	s_waitcnt lgkmcnt(0)
	v_pk_add_f32 v[174:175], v[174:175], v[178:179]
	v_pk_add_f32 v[190:191], v[190:191], v[194:195]
	v_pk_add_f32 v[206:207], v[206:207], v[210:211]
	v_pk_add_f32 v[222:223], v[222:223], v[226:227]
	ds_bpermute_b32 v179, v155, v175
	ds_bpermute_b32 v178, v155, v174
	ds_bpermute_b32 v195, v155, v191
	ds_bpermute_b32 v194, v155, v190
	ds_bpermute_b32 v211, v155, v207
	ds_bpermute_b32 v210, v155, v206
	ds_bpermute_b32 v227, v155, v223
	ds_bpermute_b32 v226, v155, v222
	s_waitcnt lgkmcnt(0)
	v_pk_add_f32 v[174:175], v[174:175], v[178:179]
	v_pk_add_f32 v[190:191], v[190:191], v[194:195]
	v_pk_add_f32 v[206:207], v[206:207], v[210:211]
	v_pk_add_f32 v[222:223], v[222:223], v[226:227]
	v_pk_fma_f32 v[174:175], v[174:175], s[36:37], v[166:167] op_sel_hi:[1,0,0]
	v_pk_fma_f32 v[190:191], v[190:191], s[36:37], v[166:167] op_sel_hi:[1,0,0]
	v_pk_fma_f32 v[206:207], v[206:207], s[36:37], v[166:167] op_sel_hi:[1,0,0]
	v_pk_fma_f32 v[222:223], v[222:223], s[36:37], v[166:167] op_sel_hi:[1,0,0]
	v_mul_f32_e32 v178, 0x4b800000, v175
	v_cmp_gt_f32_e64 s[8:9], s69, v175
	v_cmp_gt_f32_e32 vcc, s69, v174
	s_nop 0
	v_cndmask_b32_e64 v175, v175, v178, s[8:9]
	v_rsq_f32_e32 v175, v175
	s_nop 0
	v_mul_f32_e32 v178, 0x45800000, v175
	v_cndmask_b32_e64 v158, v175, v178, s[8:9]
	v_mul_f32_e32 v175, 0x4b800000, v174
	v_cndmask_b32_e32 v174, v174, v175, vcc
	v_rsq_f32_e32 v174, v174
	s_nop 0
	v_mul_f32_e32 v175, 0x45800000, v174
	v_cndmask_b32_e32 v156, v174, v175, vcc
	v_mul_f32_e32 v194, 0x4b800000, v191
	v_cmp_gt_f32_e64 s[8:9], s69, v191
	v_cmp_gt_f32_e32 vcc, s69, v190
	s_nop 0
	v_cndmask_b32_e64 v191, v191, v194, s[8:9]
	v_rsq_f32_e32 v191, v191
	s_nop 0
	v_mul_f32_e32 v194, 0x45800000, v191
	v_cndmask_b32_e64 v162, v191, v194, s[8:9]
	v_mul_f32_e32 v191, 0x4b800000, v190
	v_cndmask_b32_e32 v190, v190, v191, vcc
	v_rsq_f32_e32 v190, v190
	s_nop 0
	v_mul_f32_e32 v191, 0x45800000, v190
	v_cndmask_b32_e32 v160, v190, v191, vcc
	v_mul_f32_e32 v210, 0x4b800000, v207
	v_cmp_gt_f32_e64 s[8:9], s69, v207
	v_cmp_gt_f32_e32 vcc, s69, v206
	s_nop 0
	v_cndmask_b32_e64 v207, v207, v210, s[8:9]
	v_rsq_f32_e32 v207, v207
	s_nop 0
	v_mul_f32_e32 v210, 0x45800000, v207
	v_cndmask_b32_e64 v168, v207, v210, s[8:9]
	v_mul_f32_e32 v207, 0x4b800000, v206
	v_cndmask_b32_e32 v206, v206, v207, vcc
	v_rsq_f32_e32 v206, v206
	s_nop 0
	v_mul_f32_e32 v207, 0x45800000, v206
	v_cndmask_b32_e32 v164, v206, v207, vcc
	v_mul_f32_e32 v226, 0x4b800000, v223
	v_cmp_gt_f32_e64 s[8:9], s69, v223
	v_cmp_gt_f32_e32 vcc, s69, v222
	s_nop 0
	v_cndmask_b32_e64 v223, v223, v226, s[8:9]
	v_rsq_f32_e32 v223, v223
	s_nop 0
	v_mul_f32_e32 v226, 0x45800000, v223
	v_cndmask_b32_e64 v132, v223, v226, s[8:9]
	v_mul_f32_e32 v223, 0x4b800000, v222
	v_cndmask_b32_e32 v222, v222, v223, vcc
	v_rsq_f32_e32 v222, v222
	s_nop 0
	v_mul_f32_e32 v223, 0x45800000, v222
	v_cndmask_b32_e32 v130, v222, v223, vcc
	s_mov_b64 s[8:9], -1
	s_cmp_gt_i32 s70, 47
	s_cbranch_scc1 .LBB0_123
	s_andn2_b64 vcc, exec, s[8:9]
	s_cbranch_vccz .LBB0_126
